# ssd_prompt: wave-to-row-block roles permuted (w>=4 -> 11-w) so that each SIMD's wave pair carries equal causal work
# speedup vs baseline: 1.0138x; 1.0029x over previous
.LBB0_459:
	s_bfe_u32 s62, s61, 0x50001
	s_lshl_b32 s2, s62, 2
	v_readlane_b32 s4, v237, 44
	v_mov_b32_e32 v3, v172
	v_lshrrev_b32_e32 v1, 6, v3
	v_sub_u32_e32 v4, 11, v1
	v_cmp_gt_u32_e32 vcc, 4, v1
	s_nop 1
	v_cndmask_b32_e32 v1, v4, v1, vcc
	v_and_b32_e32 v3, 63, v3
	v_lshl_or_b32 v3, v1, 6, v3
	v_mov_b32_e32 v0, s2
	v_readlane_b32 s8, v237, 48
	v_readlane_b32 s9, v237, 49
	v_readlane_b32 s6, v237, 46
	v_readlane_b32 s7, v237, 47
	v_readlane_b32 s10, v237, 50
	v_readlane_b32 s11, v237, 51
	s_nop 0
	global_load_dword v9, v0, s[8:9]
	s_nop 0
	global_load_dword v71, v0, s[6:7]
	s_nop 0
	global_load_dword v68, v0, s[10:11]
	s_movk_i32 s0, 0x880
	v_readfirstlane_b32 s6, v3
	v_cmp_gt_i32_e32 vcc, s0, v3
	v_readlane_b32 s5, v237, 45
	v_readlane_b32 s12, v237, 52
	v_readlane_b32 s13, v237, 53
	v_readlane_b32 s14, v237, 54
	v_readlane_b32 s15, v237, 55
	v_readlane_b32 s16, v237, 56
	v_readlane_b32 s17, v237, 57
	v_readlane_b32 s18, v237, 58
	v_readlane_b32 s19, v237, 59
	s_and_saveexec_b64 s[0:1], vcc
	s_cbranch_execz .LBB0_462
	v_add_u32_e32 v0, 0xfffffe00, v3
	s_waitcnt lgkmcnt(0)
	v_lshl_add_u32 v1, v3, 2, s59
	s_mov_b64 s[4:5], 0
